# attnB loop: counted wait at the iteration top (lgkmcnt(8): only the V fragments of the first four MFMAs), second prefetch group left in flight
# baseline (speedup 1.0000x reference)
.Lb_loop:
	s_waitcnt lgkmcnt(8)
	v_mfma_f32_32x32x16_bf16 v[32:47], v[192:195], v[224:227], v[32:47]
	v_mfma_f32_32x32x16_bf16 v[48:63], v[196:199], v[224:227], v[48:63]
	ds_read_b128 v[96:99], v146 offset:33280
	ds_read_b128 v[100:103], v147 offset:33280
	ds_read_b128 v[104:107], v148 offset:33280
	ds_read_b128 v[108:111], v149 offset:33280
	v_mfma_f32_32x32x16_bf16 v[16:31], v[200:203], v[224:227], v[16:31]
	v_exp_f32_e32 v240, v80
	v_exp_f32_e32 v241, v81
	v_exp_f32_e32 v242, v82
	v_mfma_f32_32x32x16_bf16 v[0:15], v[204:207], v[224:227], v[0:15]
	v_exp_f32_e32 v243, v83
	v_exp_f32_e32 v244, v84
	v_exp_f32_e32 v245, v85
	s_waitcnt lgkmcnt(0)
	v_mfma_f32_32x32x16_bf16 v[112:127], v[96:99], v[128:131], v[64:79]
	ds_read_b128 v[96:99], v146 offset:37376
	ds_read_b64_tr_b16 v[192:193], v179 offset:18688
	ds_read_b64_tr_b16 v[194:195], v179 offset:19200
	v_add_f32_e32 v145, v240, v241
	v_cvt_pk_bf16_f32 v232, v240, v241
	v_exp_f32_e32 v246, v86
	v_exp_f32_e32 v247, v87
	v_mfma_f32_32x32x16_bf16 v[112:127], v[100:103], v[132:135], v[112:127]
	ds_read_b128 v[100:103], v147 offset:37376
	ds_read_b64_tr_b16 v[196:197], v179 offset:22848
	ds_read_b64_tr_b16 v[198:199], v179 offset:23360
	s_add_i32 s0, s50, 0xffff8000
	s_and_b32 s0, s0, 0x1f8000
	s_lshl_b32 s4, s0, 1
	s_add_i32 m0, s41, 0x18600
	s_nop 0
	buffer_load_dwordx4 v250, s[8:11], s4 offen lds
	s_add_i32 m0, s41, 0x1a600
	s_nop 0
	buffer_load_dwordx4 v250, s[8:11], s4 offen offset:128 lds
	v_add_f32_e32 v145, v145, v242
	v_add_f32_e32 v145, v145, v243
	v_cvt_pk_bf16_f32 v233, v242, v243
	v_exp_f32_e32 v240, v88
	v_mfma_f32_32x32x16_bf16 v[112:127], v[104:107], v[136:139], v[112:127]
	ds_read_b128 v[104:107], v148 offset:37376
	ds_read_b64_tr_b16 v[200:201], v179 offset:27008
	ds_read_b64_tr_b16 v[202:203], v179 offset:27520
	v_exp_f32_e32 v241, v89
	v_add_f32_e32 v145, v145, v244
	v_add_f32_e32 v145, v145, v245
	v_cvt_pk_bf16_f32 v234, v244, v245
	v_exp_f32_e32 v242, v90
	v_mfma_f32_32x32x16_bf16 v[112:127], v[108:111], v[140:143], v[112:127]
	ds_read_b128 v[108:111], v149 offset:37376
	ds_read_b64_tr_b16 v[204:205], v179 offset:31168
	ds_read_b64_tr_b16 v[206:207], v179 offset:31680
	s_add_i32 m0, s43, 0x18600
	s_nop 0
	buffer_load_dwordx4 v251, s[12:15], s4 offen lds
	s_add_i32 m0, s43, 0x1a600
	s_nop 0
	buffer_load_dwordx4 v251, s[12:15], s4 offen offset:128 lds
	v_exp_f32_e32 v243, v91
	v_add_f32_e32 v145, v145, v246
	v_add_f32_e32 v145, v145, v247
	v_cvt_pk_bf16_f32 v235, v246, v247
	v_mfma_f32_32x32x16_bf16 v[32:47], v[208:211], v[228:231], v[32:47]
	ds_read_b64_tr_b16 v[208:209], v179 offset:19712
	ds_read_b64_tr_b16 v[210:211], v179 offset:20224
	v_exp_f32_e32 v244, v92
	v_exp_f32_e32 v245, v93
	v_add_f32_e32 v145, v145, v240
	v_add_f32_e32 v145, v145, v241
	v_mfma_f32_32x32x16_bf16 v[48:63], v[212:215], v[228:231], v[48:63]
	ds_read_b64_tr_b16 v[212:213], v179 offset:23872
	ds_read_b64_tr_b16 v[214:215], v179 offset:24384
	v_cvt_pk_bf16_f32 v236, v240, v241
	v_exp_f32_e32 v246, v94
	v_exp_f32_e32 v247, v95
	v_mfma_f32_32x32x16_bf16 v[16:31], v[216:219], v[228:231], v[16:31]
	ds_read_b64_tr_b16 v[216:217], v179 offset:28032
	ds_read_b64_tr_b16 v[218:219], v179 offset:28544
	v_add_f32_e32 v145, v145, v242
	v_add_f32_e32 v145, v145, v243
	v_cvt_pk_bf16_f32 v237, v242, v243
	v_add_f32_e32 v145, v145, v244
	v_add_f32_e32 v145, v145, v245
	v_cvt_pk_bf16_f32 v238, v244, v245
	v_mfma_f32_32x32x16_bf16 v[0:15], v[220:223], v[228:231], v[0:15]
	ds_read_b64_tr_b16 v[220:221], v179 offset:32192
	ds_read_b64_tr_b16 v[222:223], v179 offset:32704
	v_add_f32_e32 v145, v145, v246
	v_add_f32_e32 v249, v145, v247
	v_cvt_pk_bf16_f32 v239, v246, v247
	v_add_f32_e32 v249, v248, v249
	v_cmp_lt_f32_e32 vcc, s3, v249
	v_add_f32_e32 v191, v191, v249
	s_waitcnt lgkmcnt(8)
	v_mfma_f32_32x32x16_bf16 v[80:95], v[96:99], v[128:131], v[64:79]
	v_exp_f32_e32 v240, v112
	v_exp_f32_e32 v241, v113
	v_exp_f32_e32 v242, v114
	v_mfma_f32_32x32x16_bf16 v[80:95], v[100:103], v[132:135], v[80:95]
	v_exp_f32_e32 v243, v115
	v_exp_f32_e32 v244, v116
	v_exp_f32_e32 v245, v117
	v_mfma_f32_32x32x16_bf16 v[80:95], v[104:107], v[136:139], v[80:95]
	v_add_f32_e32 v145, v240, v241
	v_cvt_pk_bf16_f32 v224, v240, v241
	v_exp_f32_e32 v246, v118
	v_mfma_f32_32x32x16_bf16 v[80:95], v[108:111], v[140:143], v[80:95]
	v_exp_f32_e32 v247, v119
	v_add_f32_e32 v145, v145, v242
	v_add_f32_e32 v145, v145, v243
	v_cvt_pk_bf16_f32 v225, v242, v243
	v_exp_f32_e32 v240, v120
	v_mfma_f32_32x32x16_bf16 v[32:47], v[192:195], v[232:235], v[32:47]
	ds_read_b64_tr_b16 v[192:193], v180 offset:0
	ds_read_b64_tr_b16 v[194:195], v180 offset:512
	v_exp_f32_e32 v241, v121
	v_add_f32_e32 v145, v145, v244
	v_add_f32_e32 v145, v145, v245
	v_cvt_pk_bf16_f32 v226, v244, v245
	v_mfma_f32_32x32x16_bf16 v[48:63], v[196:199], v[232:235], v[48:63]
	ds_read_b64_tr_b16 v[196:197], v180 offset:4160
	ds_read_b64_tr_b16 v[198:199], v180 offset:4672
	v_exp_f32_e32 v242, v122
	v_exp_f32_e32 v243, v123
	v_add_f32_e32 v145, v145, v246
	v_mfma_f32_32x32x16_bf16 v[16:31], v[200:203], v[232:235], v[16:31]
	ds_read_b64_tr_b16 v[200:201], v180 offset:8320
	ds_read_b64_tr_b16 v[202:203], v180 offset:8832
	v_add_f32_e32 v145, v145, v247
	v_cvt_pk_bf16_f32 v227, v246, v247
	v_exp_f32_e32 v244, v124
	v_exp_f32_e32 v245, v125
	v_mfma_f32_32x32x16_bf16 v[0:15], v[204:207], v[232:235], v[0:15]
	ds_read_b64_tr_b16 v[204:205], v180 offset:12480
	ds_read_b64_tr_b16 v[206:207], v180 offset:12992
	v_add_f32_e32 v145, v145, v240
	v_add_f32_e32 v145, v145, v241
	v_cvt_pk_bf16_f32 v228, v240, v241
	v_exp_f32_e32 v246, v126
	s_waitcnt lgkmcnt(8)
	v_mfma_f32_32x32x16_bf16 v[32:47], v[208:211], v[236:239], v[32:47]
	ds_read_b64_tr_b16 v[208:209], v180 offset:1024
	ds_read_b64_tr_b16 v[210:211], v180 offset:1536
	v_exp_f32_e32 v247, v127
	v_add_f32_e32 v145, v145, v242
	v_add_f32_e32 v145, v145, v243
	v_cvt_pk_bf16_f32 v229, v242, v243
	v_add_f32_e32 v145, v145, v244
	v_mfma_f32_32x32x16_bf16 v[48:63], v[212:215], v[236:239], v[48:63]
	ds_read_b64_tr_b16 v[212:213], v180 offset:5184
	ds_read_b64_tr_b16 v[214:215], v180 offset:5696
	v_add_f32_e32 v145, v145, v245
	v_cvt_pk_bf16_f32 v230, v244, v245
	v_add_f32_e32 v145, v145, v246
	v_add_f32_e32 v248, v145, v247
	v_cvt_pk_bf16_f32 v231, v246, v247
	v_mfma_f32_32x32x16_bf16 v[16:31], v[216:219], v[236:239], v[16:31]
	ds_read_b64_tr_b16 v[216:217], v180 offset:9344
	ds_read_b64_tr_b16 v[218:219], v180 offset:9856
	v_mfma_f32_32x32x16_bf16 v[0:15], v[220:223], v[236:239], v[0:15]
	ds_read_b64_tr_b16 v[220:221], v180 offset:13504
	ds_read_b64_tr_b16 v[222:223], v180 offset:14016
	s_cbranch_vccnz .Lb_rare0
.Lb_cont0:
	s_waitcnt vmcnt(4)
	s_barrier
	s_waitcnt lgkmcnt(8)
	v_mfma_f32_32x32x16_bf16 v[32:47], v[192:195], v[224:227], v[32:47]
	v_mfma_f32_32x32x16_bf16 v[48:63], v[196:199], v[224:227], v[48:63]
	ds_read_b128 v[96:99], v150 offset:0
	ds_read_b128 v[100:103], v151 offset:0
	ds_read_b128 v[104:107], v152 offset:0
	ds_read_b128 v[108:111], v153 offset:0
	v_mfma_f32_32x32x16_bf16 v[16:31], v[200:203], v[224:227], v[16:31]
	v_exp_f32_e32 v240, v80
	v_exp_f32_e32 v241, v81
	v_exp_f32_e32 v242, v82
	v_mfma_f32_32x32x16_bf16 v[0:15], v[204:207], v[224:227], v[0:15]
	v_exp_f32_e32 v243, v83
	v_exp_f32_e32 v244, v84
	v_exp_f32_e32 v245, v85
	s_waitcnt lgkmcnt(0)
	v_mfma_f32_32x32x16_bf16 v[112:127], v[96:99], v[128:131], v[64:79]
	ds_read_b128 v[96:99], v150 offset:4096
	ds_read_b64_tr_b16 v[192:193], v180 offset:2048
	ds_read_b64_tr_b16 v[194:195], v180 offset:2560
	v_add_f32_e32 v145, v240, v241
	v_cvt_pk_bf16_f32 v232, v240, v241
	v_exp_f32_e32 v246, v86
	v_exp_f32_e32 v247, v87
	v_mfma_f32_32x32x16_bf16 v[112:127], v[100:103], v[132:135], v[112:127]
	ds_read_b128 v[100:103], v151 offset:4096
	ds_read_b64_tr_b16 v[196:197], v180 offset:6208
	ds_read_b64_tr_b16 v[198:199], v180 offset:6720
	s_cmp_gt_u32 s6, 59
	s_cbranch_scc1 .Lb_pn0
	s_and_b32 s0, s50, 0x1f8000
	s_lshl_b32 s4, s0, 1
	s_add_i32 m0, s41, 0x0
	s_nop 0
	buffer_load_dwordx4 v250, s[8:11], s4 offen lds
	s_branch .Lb_po0

.Lb_cont1:
	s_waitcnt vmcnt(4)
	s_barrier
	s_waitcnt lgkmcnt(8)
	v_mfma_f32_32x32x16_bf16 v[32:47], v[192:195], v[224:227], v[32:47]
	v_mfma_f32_32x32x16_bf16 v[48:63], v[196:199], v[224:227], v[48:63]
	ds_read_b128 v[96:99], v150 offset:33280
	ds_read_b128 v[100:103], v151 offset:33280
	ds_read_b128 v[104:107], v152 offset:33280
	ds_read_b128 v[108:111], v153 offset:33280
	v_mfma_f32_32x32x16_bf16 v[16:31], v[200:203], v[224:227], v[16:31]
	v_exp_f32_e32 v240, v80
	v_exp_f32_e32 v241, v81
	v_exp_f32_e32 v242, v82
	v_mfma_f32_32x32x16_bf16 v[0:15], v[204:207], v[224:227], v[0:15]
	v_exp_f32_e32 v243, v83
	v_exp_f32_e32 v244, v84
	v_exp_f32_e32 v245, v85
	s_waitcnt lgkmcnt(0)
	v_mfma_f32_32x32x16_bf16 v[112:127], v[96:99], v[128:131], v[64:79]
	ds_read_b128 v[96:99], v150 offset:37376
	ds_read_b64_tr_b16 v[192:193], v182 offset:2048
	ds_read_b64_tr_b16 v[194:195], v182 offset:2560
	v_add_f32_e32 v145, v240, v241
	v_cvt_pk_bf16_f32 v232, v240, v241
	v_exp_f32_e32 v246, v86
	v_exp_f32_e32 v247, v87
	v_mfma_f32_32x32x16_bf16 v[112:127], v[100:103], v[132:135], v[112:127]
	ds_read_b128 v[100:103], v151 offset:37376
	ds_read_b64_tr_b16 v[196:197], v182 offset:6208
	ds_read_b64_tr_b16 v[198:199], v182 offset:6720
	s_cmp_gt_u32 s6, 59
	s_cbranch_scc1 .Lb_pn4
	s_add_i32 s0, s50, 0x8000
	s_and_b32 s0, s0, 0x1f8000
	s_lshl_b32 s4, s0, 1
	s_add_i32 m0, s41, 0x8200
	s_nop 0
	buffer_load_dwordx4 v250, s[8:11], s4 offen lds
	s_branch .Lb_po4

.Lb_cont2:
	s_waitcnt vmcnt(4)
	s_barrier
	s_cmp_gt_u32 s6, 59
	s_cbranch_scc1 .Lb_final
	s_waitcnt lgkmcnt(8)
	v_mfma_f32_32x32x16_bf16 v[32:47], v[192:195], v[224:227], v[32:47]
	v_mfma_f32_32x32x16_bf16 v[48:63], v[196:199], v[224:227], v[48:63]
	ds_read_b128 v[96:99], v146 offset:0
	ds_read_b128 v[100:103], v147 offset:0
	ds_read_b128 v[104:107], v148 offset:0
	ds_read_b128 v[108:111], v149 offset:0
	v_mfma_f32_32x32x16_bf16 v[16:31], v[200:203], v[224:227], v[16:31]
	v_exp_f32_e32 v240, v80
	v_exp_f32_e32 v241, v81
	v_exp_f32_e32 v242, v82
	v_mfma_f32_32x32x16_bf16 v[0:15], v[204:207], v[224:227], v[0:15]
	v_exp_f32_e32 v243, v83
	v_exp_f32_e32 v244, v84
	v_exp_f32_e32 v245, v85
	s_waitcnt lgkmcnt(0)
	v_mfma_f32_32x32x16_bf16 v[112:127], v[96:99], v[128:131], v[64:79]
	ds_read_b128 v[96:99], v146 offset:4096
	ds_read_b64_tr_b16 v[192:193], v182 offset:35328
	ds_read_b64_tr_b16 v[194:195], v182 offset:35840
	v_add_f32_e32 v145, v240, v241
	v_cvt_pk_bf16_f32 v232, v240, v241
	v_exp_f32_e32 v246, v86
	v_exp_f32_e32 v247, v87
	v_mfma_f32_32x32x16_bf16 v[112:127], v[100:103], v[132:135], v[112:127]
	ds_read_b128 v[100:103], v147 offset:4096
	ds_read_b64_tr_b16 v[196:197], v182 offset:39488
	ds_read_b64_tr_b16 v[198:199], v182 offset:40000
	s_add_i32 s0, s50, 0x10000
	s_and_b32 s0, s0, 0x1f8000
	s_lshl_b32 s4, s0, 1
	s_add_i32 m0, s41, 0x10400
	s_nop 0
	buffer_load_dwordx4 v250, s[8:11], s4 offen lds
	s_add_i32 m0, s41, 0x12400
	s_nop 0
	buffer_load_dwordx4 v250, s[8:11], s4 offen offset:128 lds
	v_add_f32_e32 v145, v145, v242
	v_add_f32_e32 v145, v145, v243
	v_cvt_pk_bf16_f32 v233, v242, v243
	v_exp_f32_e32 v240, v88
	v_mfma_f32_32x32x16_bf16 v[112:127], v[104:107], v[136:139], v[112:127]
	ds_read_b128 v[104:107], v148 offset:4096
	ds_read_b64_tr_b16 v[200:201], v182 offset:43648
	ds_read_b64_tr_b16 v[202:203], v182 offset:44160
	v_exp_f32_e32 v241, v89
	v_add_f32_e32 v145, v145, v244
	v_add_f32_e32 v145, v145, v245
	v_cvt_pk_bf16_f32 v234, v244, v245
	v_exp_f32_e32 v242, v90
	v_mfma_f32_32x32x16_bf16 v[112:127], v[108:111], v[140:143], v[112:127]
	ds_read_b128 v[108:111], v149 offset:4096
	ds_read_b64_tr_b16 v[204:205], v182 offset:47808
	ds_read_b64_tr_b16 v[206:207], v182 offset:48320
	s_add_i32 m0, s43, 0x10400
	s_nop 0
	buffer_load_dwordx4 v251, s[12:15], s4 offen lds
	s_add_i32 m0, s43, 0x12400
	s_nop 0
	buffer_load_dwordx4 v251, s[12:15], s4 offen offset:128 lds
	v_exp_f32_e32 v243, v91
	v_add_f32_e32 v145, v145, v246
	v_add_f32_e32 v145, v145, v247
	v_cvt_pk_bf16_f32 v235, v246, v247
	v_mfma_f32_32x32x16_bf16 v[32:47], v[208:211], v[228:231], v[32:47]
	ds_read_b64_tr_b16 v[208:209], v182 offset:36352
	ds_read_b64_tr_b16 v[210:211], v182 offset:36864
	v_exp_f32_e32 v244, v92
	v_exp_f32_e32 v245, v93
	v_add_f32_e32 v145, v145, v240
	v_add_f32_e32 v145, v145, v241
	v_mfma_f32_32x32x16_bf16 v[48:63], v[212:215], v[228:231], v[48:63]
	ds_read_b64_tr_b16 v[212:213], v182 offset:40512
	ds_read_b64_tr_b16 v[214:215], v182 offset:41024
	v_cvt_pk_bf16_f32 v236, v240, v241
	v_exp_f32_e32 v246, v94
	v_exp_f32_e32 v247, v95
	v_mfma_f32_32x32x16_bf16 v[16:31], v[216:219], v[228:231], v[16:31]
	ds_read_b64_tr_b16 v[216:217], v182 offset:44672
	ds_read_b64_tr_b16 v[218:219], v182 offset:45184
	v_add_f32_e32 v145, v145, v242
	v_add_f32_e32 v145, v145, v243
	v_cvt_pk_bf16_f32 v237, v242, v243
	v_add_f32_e32 v145, v145, v244
	v_add_f32_e32 v145, v145, v245
	v_cvt_pk_bf16_f32 v238, v244, v245
	v_mfma_f32_32x32x16_bf16 v[0:15], v[220:223], v[228:231], v[0:15]
	ds_read_b64_tr_b16 v[220:221], v182 offset:48832
	ds_read_b64_tr_b16 v[222:223], v182 offset:49344
	v_add_f32_e32 v145, v145, v246
	v_add_f32_e32 v249, v145, v247
	v_cvt_pk_bf16_f32 v239, v246, v247
	v_add_f32_e32 v249, v248, v249
	v_cmp_lt_f32_e32 vcc, s3, v249
	v_add_f32_e32 v191, v191, v249
	s_waitcnt lgkmcnt(8)
	v_mfma_f32_32x32x16_bf16 v[80:95], v[96:99], v[128:131], v[64:79]
	v_exp_f32_e32 v240, v112
	v_exp_f32_e32 v241, v113
	v_exp_f32_e32 v242, v114
	v_mfma_f32_32x32x16_bf16 v[80:95], v[100:103], v[132:135], v[80:95]
	v_exp_f32_e32 v243, v115
	v_exp_f32_e32 v244, v116
	v_exp_f32_e32 v245, v117
	v_mfma_f32_32x32x16_bf16 v[80:95], v[104:107], v[136:139], v[80:95]
	v_add_f32_e32 v145, v240, v241
	v_cvt_pk_bf16_f32 v224, v240, v241
	v_exp_f32_e32 v246, v118
	v_mfma_f32_32x32x16_bf16 v[80:95], v[108:111], v[140:143], v[80:95]
	v_exp_f32_e32 v247, v119
	v_add_f32_e32 v145, v145, v242
	v_add_f32_e32 v145, v145, v243
	v_cvt_pk_bf16_f32 v225, v242, v243
	v_exp_f32_e32 v240, v120
	v_mfma_f32_32x32x16_bf16 v[32:47], v[192:195], v[232:235], v[32:47]
	ds_read_b64_tr_b16 v[192:193], v179 offset:16640
	ds_read_b64_tr_b16 v[194:195], v179 offset:17152
	v_exp_f32_e32 v241, v121
	v_add_f32_e32 v145, v145, v244
	v_add_f32_e32 v145, v145, v245
	v_cvt_pk_bf16_f32 v226, v244, v245
	v_mfma_f32_32x32x16_bf16 v[48:63], v[196:199], v[232:235], v[48:63]
	ds_read_b64_tr_b16 v[196:197], v179 offset:20800
	ds_read_b64_tr_b16 v[198:199], v179 offset:21312
	v_exp_f32_e32 v242, v122
	v_exp_f32_e32 v243, v123
	v_add_f32_e32 v145, v145, v246
	v_mfma_f32_32x32x16_bf16 v[16:31], v[200:203], v[232:235], v[16:31]
	ds_read_b64_tr_b16 v[200:201], v179 offset:24960
	ds_read_b64_tr_b16 v[202:203], v179 offset:25472
	v_add_f32_e32 v145, v145, v247
	v_cvt_pk_bf16_f32 v227, v246, v247
	v_exp_f32_e32 v244, v124
	v_exp_f32_e32 v245, v125
	v_mfma_f32_32x32x16_bf16 v[0:15], v[204:207], v[232:235], v[0:15]
	ds_read_b64_tr_b16 v[204:205], v179 offset:29120
	ds_read_b64_tr_b16 v[206:207], v179 offset:29632
	v_add_f32_e32 v145, v145, v240
	v_add_f32_e32 v145, v145, v241
	v_cvt_pk_bf16_f32 v228, v240, v241
	v_exp_f32_e32 v246, v126
	s_waitcnt lgkmcnt(8)
	v_mfma_f32_32x32x16_bf16 v[32:47], v[208:211], v[236:239], v[32:47]
	ds_read_b64_tr_b16 v[208:209], v179 offset:17664
	ds_read_b64_tr_b16 v[210:211], v179 offset:18176
	v_exp_f32_e32 v247, v127
	v_add_f32_e32 v145, v145, v242
	v_add_f32_e32 v145, v145, v243
	v_cvt_pk_bf16_f32 v229, v242, v243
	v_add_f32_e32 v145, v145, v244
	v_mfma_f32_32x32x16_bf16 v[48:63], v[212:215], v[236:239], v[48:63]
	ds_read_b64_tr_b16 v[212:213], v179 offset:21824
	ds_read_b64_tr_b16 v[214:215], v179 offset:22336
	v_add_f32_e32 v145, v145, v245
	v_cvt_pk_bf16_f32 v230, v244, v245
	v_add_f32_e32 v145, v145, v246
	v_add_f32_e32 v248, v145, v247
	v_cvt_pk_bf16_f32 v231, v246, v247
	v_mfma_f32_32x32x16_bf16 v[16:31], v[216:219], v[236:239], v[16:31]
	ds_read_b64_tr_b16 v[216:217], v179 offset:25984
	ds_read_b64_tr_b16 v[218:219], v179 offset:26496
	v_mfma_f32_32x32x16_bf16 v[0:15], v[220:223], v[236:239], v[0:15]
	ds_read_b64_tr_b16 v[220:221], v179 offset:30144
	ds_read_b64_tr_b16 v[222:223], v179 offset:30656
	s_cbranch_vccnz .Lb_rare3
